# grid barrier: followers issue their L1 acquire-invalidate before polling (the parked workgroup refills nothing), leader signals its XCC before its own invalidate; plus the combine-phase load hoist
# speedup vs baseline: 1.0251x; 1.0156x over previous
; __device__ __forceinline__ unsigned xb_ld(unsigned* p)              { return __hip_atomic_load(p, __ATOMIC_RELAXED, __HIP_MEMORY_SCOPE_AGENT); }
; __device__ __forceinline__ unsigned xb_add(unsigned* p, unsigned v) { return __hip_atomic_fetch_add(p, v, __ATOMIC_RELAXED, __HIP_MEMORY_SCOPE_AGENT); }
; #define XB_SPIN(cond, bar) do { unsigned _sp = 0; while (cond) { __builtin_amdgcn_s_sleep(1); \
;     if ((++_sp & 255u) == 0u) { if (xb_ld(&(bar)[XB_TMO])) break; if (_sp > XB_SPIN_CAP) { atomicAdd(&(bar)[XB_TMO], 1u); break; } } } } while (0)
; __device__ __forceinline__ void xcd_barrier(const XcdBarrier& b) {
;     ...
;         const unsigned old = xb_add(&bar[XB_XSUB(b.x)], 1u);
;         const unsigned gen = old / nloc;
;         if (old + 1u == (gen + 1u) * nloc) {
;             __builtin_amdgcn_fence(__ATOMIC_RELEASE, "agent");
;             asm volatile("s_waitcnt vmcnt(0)" ::: "memory");
;             const unsigned og = xb_add(&bar[XB_TOP], 1u);
;             const unsigned tg = og / nx;
;             if (og + 1u == (tg + 1u) * nx) xb_add(&bar[XB_TOPGEN], 1u);
;             else XB_SPIN(xb_ld(&bar[XB_TOPGEN]) == tg, bar);
;             __builtin_amdgcn_fence(__ATOMIC_ACQUIRE, "agent");
;             xb_add(&bar[XB_XGEN(b.x)], 1u);
;             asm volatile("s_waitcnt vmcnt(0)" ::: "memory");
;         } else {
;             XB_SPIN(xb_ld(&bar[XB_XGEN(b.x)]) == gen, bar);
.LBB0_103:
	s_or_b64 exec, exec, s[12:13]
	v_cvt_f32_u32_e32 v4, v2
	s_waitcnt vmcnt(0)
	v_readfirstlane_b32 s8, v3
	v_sub_u32_e32 v3, 0, v2
	v_rcp_iflag_f32_e32 v4, v4
	v_add_u32_e32 v5, s8, v1
	v_mul_f32_e32 v4, 0x4f7ffffe, v4
	v_cvt_u32_f32_e32 v4, v4
	v_mul_lo_u32 v1, v3, v4
	v_mul_hi_u32 v1, v4, v1
	v_add_u32_e32 v1, v4, v1
	v_mul_hi_u32 v1, v5, v1
	v_mul_lo_u32 v3, v1, v2
	v_sub_u32_e32 v3, v5, v3
	v_add_u32_e32 v4, 1, v1
	v_cmp_ge_u32_e32 vcc, v3, v2
	s_nop 1
	v_cndmask_b32_e32 v1, v1, v4, vcc
	v_sub_u32_e32 v4, v3, v2
	v_cndmask_b32_e32 v3, v3, v4, vcc
	v_add_u32_e32 v4, 1, v1
	v_cmp_ge_u32_e32 vcc, v3, v2
	v_add_u32_e32 v3, 1, v5
	s_nop 0
	v_cndmask_b32_e32 v1, v1, v4, vcc
	v_mul_lo_u32 v4, v2, v1
	v_add_u32_e32 v2, v4, v2
	v_cmp_ne_u32_e32 vcc, v3, v2
	s_and_saveexec_b64 s[8:9], vcc
	s_xor_b64 s[8:9], exec, s[8:9]
	s_cbranch_execz .LBB0_119
	buffer_inv sc1
	s_waitcnt lgkmcnt(0)
	v_mov_b32_e32 v0, 0x2000
	global_load_dword v0, v0, s[6:7] offset:1024 sc1
	s_add_u32 s16, s6, 0x2400
	s_addc_u32 s17, s7, 0
	s_waitcnt vmcnt(0)
	v_cmp_eq_u32_e32 vcc, v0, v1
	s_and_saveexec_b64 s[12:13], vcc
	s_cbranch_execz .LBB0_118
	s_add_u32 s14, s2, 0x15d20200
	s_addc_u32 s15, s3, 0
	s_mov_b32 s30, 1
	s_mov_b64 s[18:19], 0
	v_mov_b32_e32 v0, 0
	s_branch .LBB0_107

; __device__ __forceinline__ unsigned xb_ld(unsigned* p)              { return __hip_atomic_load(p, __ATOMIC_RELAXED, __HIP_MEMORY_SCOPE_AGENT); }
; #define XB_SPIN(cond, bar) do { unsigned _sp = 0; while (cond) { __builtin_amdgcn_s_sleep(1); \
;     if ((++_sp & 255u) == 0u) { if (xb_ld(&(bar)[XB_TMO])) break; if (_sp > XB_SPIN_CAP) { atomicAdd(&(bar)[XB_TMO], 1u); break; } } } } while (0)
; __device__ __forceinline__ void xcd_barrier(const XcdBarrier& b) {
;     ...
;             XB_SPIN(xb_ld(&bar[XB_XGEN(b.x)]) == gen, bar);
;             __builtin_amdgcn_fence(__ATOMIC_ACQUIRE, "agent");
;             asm volatile("s_waitcnt vmcnt(0)" ::: "memory");
.LBB0_118:
	s_or_b64 exec, exec, s[12:13]
	s_waitcnt vmcnt(0)
	s_waitcnt vmcnt(0)

; __device__ __forceinline__ unsigned xb_add(unsigned* p, unsigned v) { return __hip_atomic_fetch_add(p, v, __ATOMIC_RELAXED, __HIP_MEMORY_SCOPE_AGENT); }
; __device__ __forceinline__ void xcd_barrier(const XcdBarrier& b) {
;     ...
;             __builtin_amdgcn_fence(__ATOMIC_ACQUIRE, "agent");
;             xb_add(&bar[XB_XGEN(b.x)], 1u);
;             asm volatile("s_waitcnt vmcnt(0)" ::: "memory");
.LBB0_136:
	s_or_b64 exec, exec, s[8:9]
	s_mov_b64 s[8:9], exec
	v_mbcnt_lo_u32_b32 v0, s8, 0
	v_mbcnt_hi_u32_b32 v0, s9, v0
	v_cmp_eq_u32_e32 vcc, 0, v0
	s_waitcnt vmcnt(0)
	s_and_saveexec_b64 s[12:13], vcc
	s_cbranch_execz .LBB0_138
	s_bcnt1_i32_b64 s8, s[8:9]
	v_mov_b32_e32 v0, 0x2000
	v_mov_b32_e32 v1, s8
	global_atomic_add v0, v1, s[6:7] offset:1024
.LBB0_138:
	s_or_b64 exec, exec, s[12:13]
	buffer_inv sc1
	s_waitcnt vmcnt(0)

; __device__ __forceinline__ unsigned xb_ld(unsigned* p)              { return __hip_atomic_load(p, __ATOMIC_RELAXED, __HIP_MEMORY_SCOPE_AGENT); }
; #define XB_SPIN(cond, bar) do { unsigned _sp = 0; while (cond) { __builtin_amdgcn_s_sleep(1); \
;     if ((++_sp & 255u) == 0u) { if (xb_ld(&(bar)[XB_TMO])) break; if (_sp > XB_SPIN_CAP) { atomicAdd(&(bar)[XB_TMO], 1u); break; } } } } while (0)
; __device__ __forceinline__ void xcd_barrier(const XcdBarrier& b) {
;     ...
;         } else {
;             XB_SPIN(xb_ld(&bar[XB_XGEN(b.x)]) == gen, bar);
;             __builtin_amdgcn_fence(__ATOMIC_ACQUIRE, "agent");
;             asm volatile("s_waitcnt vmcnt(0)" ::: "memory");
;         }
.LBB0_141:
	s_or_b64 exec, exec, s[40:41]
	buffer_inv sc1
	s_waitcnt vmcnt(0)

; __device__ __forceinline__ unsigned xb_ld(unsigned* p)              { return __hip_atomic_load(p, __ATOMIC_RELAXED, __HIP_MEMORY_SCOPE_AGENT); }
; __device__ __forceinline__ unsigned xb_add(unsigned* p, unsigned v) { return __hip_atomic_fetch_add(p, v, __ATOMIC_RELAXED, __HIP_MEMORY_SCOPE_AGENT); }
; #define XB_SPIN(cond, bar) do { unsigned _sp = 0; while (cond) { __builtin_amdgcn_s_sleep(1); \
;     if ((++_sp & 255u) == 0u) { if (xb_ld(&(bar)[XB_TMO])) break; if (_sp > XB_SPIN_CAP) { atomicAdd(&(bar)[XB_TMO], 1u); break; } } } } while (0)
; __device__ __forceinline__ void xcd_barrier(const XcdBarrier& b) {
;     ...
;         const unsigned old = xb_add(&bar[XB_XSUB(b.x)], 1u);
;         const unsigned gen = old / nloc;
;         if (old + 1u == (gen + 1u) * nloc) {
;             __builtin_amdgcn_fence(__ATOMIC_RELEASE, "agent");
;             asm volatile("s_waitcnt vmcnt(0)" ::: "memory");
;             const unsigned og = xb_add(&bar[XB_TOP], 1u);
;             const unsigned tg = og / nx;
;             if (og + 1u == (tg + 1u) * nx) xb_add(&bar[XB_TOPGEN], 1u);
;             else XB_SPIN(xb_ld(&bar[XB_TOPGEN]) == tg, bar);
;             __builtin_amdgcn_fence(__ATOMIC_ACQUIRE, "agent");
;             xb_add(&bar[XB_XGEN(b.x)], 1u);
;             asm volatile("s_waitcnt vmcnt(0)" ::: "memory");
;         } else {
;             XB_SPIN(xb_ld(&bar[XB_XGEN(b.x)]) == gen, bar);
.LBB0_225:
	s_or_b64 exec, exec, s[42:43]
	v_cvt_f32_u32_e32 v5, v3
	s_waitcnt vmcnt(0)
	v_readfirstlane_b32 s3, v4
	v_sub_u32_e32 v4, 0, v3
	v_rcp_iflag_f32_e32 v5, v5
	v_add_u32_e32 v6, s3, v0
	v_mul_f32_e32 v5, 0x4f7ffffe, v5
	v_cvt_u32_f32_e32 v5, v5
	v_mul_lo_u32 v0, v4, v5
	v_mul_hi_u32 v0, v5, v0
	v_add_u32_e32 v0, v5, v0
	v_mul_hi_u32 v0, v6, v0
	v_mul_lo_u32 v4, v0, v3
	v_sub_u32_e32 v4, v6, v4
	v_add_u32_e32 v5, 1, v0
	v_cmp_ge_u32_e32 vcc, v4, v3
	s_nop 1
	v_cndmask_b32_e32 v0, v0, v5, vcc
	v_sub_u32_e32 v5, v4, v3
	v_cndmask_b32_e32 v4, v4, v5, vcc
	v_add_u32_e32 v5, 1, v0
	v_cmp_ge_u32_e32 vcc, v4, v3
	v_add_u32_e32 v4, 1, v6
	s_nop 0
	v_cndmask_b32_e32 v0, v0, v5, vcc
	v_mul_lo_u32 v5, v3, v0
	v_add_u32_e32 v3, v5, v3
	v_cmp_ne_u32_e32 vcc, v4, v3
	s_and_saveexec_b64 s[12:13], vcc
	s_xor_b64 s[42:43], exec, s[12:13]
	s_cbranch_execz .LBB0_239
	buffer_inv sc1
	v_readlane_b32 s12, v255, 10
	v_readlane_b32 s13, v255, 11
	s_waitcnt lgkmcnt(0)
	s_nop 3
	global_load_dword v2, v1, s[12:13] sc1
	s_waitcnt vmcnt(0)
	v_cmp_eq_u32_e32 vcc, v2, v0
	s_and_saveexec_b64 s[44:45], vcc
	s_cbranch_execz .LBB0_238
	s_mov_b32 s3, 1
	s_mov_b64 s[46:47], 0
	s_branch .LBB0_229

; __device__ __forceinline__ unsigned xb_ld(unsigned* p)              { return __hip_atomic_load(p, __ATOMIC_RELAXED, __HIP_MEMORY_SCOPE_AGENT); }
; #define XB_SPIN(cond, bar) do { unsigned _sp = 0; while (cond) { __builtin_amdgcn_s_sleep(1); \
;     if ((++_sp & 255u) == 0u) { if (xb_ld(&(bar)[XB_TMO])) break; if (_sp > XB_SPIN_CAP) { atomicAdd(&(bar)[XB_TMO], 1u); break; } } } } while (0)
; __device__ __forceinline__ void xcd_barrier(const XcdBarrier& b) {
;     ...
;             XB_SPIN(xb_ld(&bar[XB_XGEN(b.x)]) == gen, bar);
;             __builtin_amdgcn_fence(__ATOMIC_ACQUIRE, "agent");
;             asm volatile("s_waitcnt vmcnt(0)" ::: "memory");
.LBB0_238:
	s_or_b64 exec, exec, s[44:45]
	s_waitcnt vmcnt(0)
	s_waitcnt vmcnt(0)

; __device__ __forceinline__ unsigned xb_add(unsigned* p, unsigned v) { return __hip_atomic_fetch_add(p, v, __ATOMIC_RELAXED, __HIP_MEMORY_SCOPE_AGENT); }
; __device__ __forceinline__ void xcd_barrier(const XcdBarrier& b) {
;     ...
;             __builtin_amdgcn_fence(__ATOMIC_ACQUIRE, "agent");
;             xb_add(&bar[XB_XGEN(b.x)], 1u);
;             asm volatile("s_waitcnt vmcnt(0)" ::: "memory");
.LBB0_256:
	s_or_b64 exec, exec, s[42:43]
	s_mov_b64 s[42:43], exec
	v_mbcnt_lo_u32_b32 v0, s42, 0
	v_mbcnt_hi_u32_b32 v0, s43, v0
	v_cmp_eq_u32_e32 vcc, 0, v0
	s_waitcnt vmcnt(0)
	s_and_saveexec_b64 s[44:45], vcc
	s_cbranch_execz .LBB0_258
	s_bcnt1_i32_b64 s3, s[42:43]
	v_readlane_b32 s12, v255, 10
	v_mov_b32_e32 v0, s3
	v_readlane_b32 s13, v255, 11
	s_nop 4
	global_atomic_add v1, v0, s[12:13]
.LBB0_258:
	s_or_b64 exec, exec, s[44:45]
	buffer_inv sc1
	s_waitcnt vmcnt(0)

; __device__ __forceinline__ unsigned xb_ld(unsigned* p)              { return __hip_atomic_load(p, __ATOMIC_RELAXED, __HIP_MEMORY_SCOPE_AGENT); }
; __device__ __forceinline__ unsigned xb_add(unsigned* p, unsigned v) { return __hip_atomic_fetch_add(p, v, __ATOMIC_RELAXED, __HIP_MEMORY_SCOPE_AGENT); }
; #define XB_SPIN(cond, bar) do { unsigned _sp = 0; while (cond) { __builtin_amdgcn_s_sleep(1); \
;     if ((++_sp & 255u) == 0u) { if (xb_ld(&(bar)[XB_TMO])) break; if (_sp > XB_SPIN_CAP) { atomicAdd(&(bar)[XB_TMO], 1u); break; } } } } while (0)
; __device__ __forceinline__ void xcd_barrier(const XcdBarrier& b) {
;     ...
;         const unsigned old = xb_add(&bar[XB_XSUB(b.x)], 1u);
;         const unsigned gen = old / nloc;
;         if (old + 1u == (gen + 1u) * nloc) {
;             __builtin_amdgcn_fence(__ATOMIC_RELEASE, "agent");
;             asm volatile("s_waitcnt vmcnt(0)" ::: "memory");
;             const unsigned og = xb_add(&bar[XB_TOP], 1u);
;             const unsigned tg = og / nx;
;             if (og + 1u == (tg + 1u) * nx) xb_add(&bar[XB_TOPGEN], 1u);
;             else XB_SPIN(xb_ld(&bar[XB_TOPGEN]) == tg, bar);
;             __builtin_amdgcn_fence(__ATOMIC_ACQUIRE, "agent");
;             xb_add(&bar[XB_XGEN(b.x)], 1u);
;             asm volatile("s_waitcnt vmcnt(0)" ::: "memory");
;         } else {
;             XB_SPIN(xb_ld(&bar[XB_XGEN(b.x)]) == gen, bar);
.LBB0_302:
	s_or_b64 exec, exec, s[38:39]
	v_cvt_f32_u32_e32 v5, v3
	s_waitcnt vmcnt(0)
	v_readfirstlane_b32 s12, v4
	v_sub_u32_e32 v4, 0, v3
	v_rcp_iflag_f32_e32 v5, v5
	v_add_u32_e32 v6, s12, v0
	v_mul_f32_e32 v5, 0x4f7ffffe, v5
	v_cvt_u32_f32_e32 v5, v5
	v_mul_lo_u32 v0, v4, v5
	v_mul_hi_u32 v0, v5, v0
	v_add_u32_e32 v0, v5, v0
	v_mul_hi_u32 v0, v6, v0
	v_mul_lo_u32 v4, v0, v3
	v_sub_u32_e32 v4, v6, v4
	v_add_u32_e32 v5, 1, v0
	v_cmp_ge_u32_e32 vcc, v4, v3
	s_nop 1
	v_cndmask_b32_e32 v0, v0, v5, vcc
	v_sub_u32_e32 v5, v4, v3
	v_cndmask_b32_e32 v4, v4, v5, vcc
	v_add_u32_e32 v5, 1, v0
	v_cmp_ge_u32_e32 vcc, v4, v3
	v_add_u32_e32 v4, 1, v6
	s_nop 0
	v_cndmask_b32_e32 v0, v0, v5, vcc
	v_mul_lo_u32 v5, v3, v0
	v_add_u32_e32 v3, v5, v3
	v_cmp_ne_u32_e32 vcc, v4, v3
	s_and_saveexec_b64 s[12:13], vcc
	s_xor_b64 s[38:39], exec, s[12:13]
	s_cbranch_execz .LBB0_316
	buffer_inv sc1
	v_readlane_b32 s12, v255, 10
	v_readlane_b32 s13, v255, 11
	s_waitcnt lgkmcnt(0)
	s_nop 3
	global_load_dword v2, v1, s[12:13] sc1
	s_waitcnt vmcnt(0)
	v_cmp_eq_u32_e32 vcc, v2, v0
	s_and_saveexec_b64 s[40:41], vcc
	s_cbranch_execz .LBB0_315
	s_mov_b32 s12, 1
	s_mov_b64 s[42:43], 0
	s_branch .LBB0_306

; __device__ __forceinline__ unsigned xb_ld(unsigned* p)              { return __hip_atomic_load(p, __ATOMIC_RELAXED, __HIP_MEMORY_SCOPE_AGENT); }
; #define XB_SPIN(cond, bar) do { unsigned _sp = 0; while (cond) { __builtin_amdgcn_s_sleep(1); \
;     if ((++_sp & 255u) == 0u) { if (xb_ld(&(bar)[XB_TMO])) break; if (_sp > XB_SPIN_CAP) { atomicAdd(&(bar)[XB_TMO], 1u); break; } } } } while (0)
; __device__ __forceinline__ void xcd_barrier(const XcdBarrier& b) {
;     ...
;             XB_SPIN(xb_ld(&bar[XB_XGEN(b.x)]) == gen, bar);
;             __builtin_amdgcn_fence(__ATOMIC_ACQUIRE, "agent");
;             asm volatile("s_waitcnt vmcnt(0)" ::: "memory");
.LBB0_315:
	s_or_b64 exec, exec, s[40:41]
	s_waitcnt vmcnt(0)
	s_waitcnt vmcnt(0)

; __device__ __forceinline__ unsigned xb_add(unsigned* p, unsigned v) { return __hip_atomic_fetch_add(p, v, __ATOMIC_RELAXED, __HIP_MEMORY_SCOPE_AGENT); }
; __device__ __forceinline__ void xcd_barrier(const XcdBarrier& b) {
;     ...
;             __builtin_amdgcn_fence(__ATOMIC_ACQUIRE, "agent");
;             xb_add(&bar[XB_XGEN(b.x)], 1u);
.LBB0_333:
	s_or_b64 exec, exec, s[38:39]
	s_mov_b64 s[38:39], exec
	v_mbcnt_lo_u32_b32 v0, s38, 0
	v_mbcnt_hi_u32_b32 v0, s39, v0
	v_cmp_eq_u32_e32 vcc, 0, v0
	s_waitcnt vmcnt(0)
	s_and_saveexec_b64 s[40:41], vcc
	s_cbranch_execz .LBB0_335
	s_bcnt1_i32_b64 s12, s[38:39]
	v_mov_b32_e32 v0, s12
	v_readlane_b32 s12, v255, 10
	v_readlane_b32 s13, v255, 11
	s_nop 4
	global_atomic_add v1, v0, s[12:13]

; __device__ __forceinline__ unsigned xb_ld(unsigned* p)              { return __hip_atomic_load(p, __ATOMIC_RELAXED, __HIP_MEMORY_SCOPE_AGENT); }
; __device__ __forceinline__ unsigned xb_add(unsigned* p, unsigned v) { return __hip_atomic_fetch_add(p, v, __ATOMIC_RELAXED, __HIP_MEMORY_SCOPE_AGENT); }
; #define XB_SPIN(cond, bar) do { unsigned _sp = 0; while (cond) { __builtin_amdgcn_s_sleep(1); \
;     if ((++_sp & 255u) == 0u) { if (xb_ld(&(bar)[XB_TMO])) break; if (_sp > XB_SPIN_CAP) { atomicAdd(&(bar)[XB_TMO], 1u); break; } } } } while (0)
; __device__ __forceinline__ void xcd_barrier(const XcdBarrier& b) {
;     ...
;         const unsigned old = xb_add(&bar[XB_XSUB(b.x)], 1u);
;         const unsigned gen = old / nloc;
;         if (old + 1u == (gen + 1u) * nloc) {
;             __builtin_amdgcn_fence(__ATOMIC_RELEASE, "agent");
;             asm volatile("s_waitcnt vmcnt(0)" ::: "memory");
;             const unsigned og = xb_add(&bar[XB_TOP], 1u);
;             const unsigned tg = og / nx;
;             if (og + 1u == (tg + 1u) * nx) xb_add(&bar[XB_TOPGEN], 1u);
;             else XB_SPIN(xb_ld(&bar[XB_TOPGEN]) == tg, bar);
;             __builtin_amdgcn_fence(__ATOMIC_ACQUIRE, "agent");
;             xb_add(&bar[XB_XGEN(b.x)], 1u);
;             asm volatile("s_waitcnt vmcnt(0)" ::: "memory");
;         } else {
;             XB_SPIN(xb_ld(&bar[XB_XGEN(b.x)]) == gen, bar);
.LBB0_476:
	s_or_b64 exec, exec, s[38:39]
	v_cvt_f32_u32_e32 v5, v3
	s_waitcnt vmcnt(0)
	v_readfirstlane_b32 s3, v4
	v_sub_u32_e32 v4, 0, v3
	v_rcp_iflag_f32_e32 v5, v5
	v_add_u32_e32 v6, s3, v0
	v_mul_f32_e32 v5, 0x4f7ffffe, v5
	v_cvt_u32_f32_e32 v5, v5
	v_mul_lo_u32 v0, v4, v5
	v_mul_hi_u32 v0, v5, v0
	v_add_u32_e32 v0, v5, v0
	v_mul_hi_u32 v0, v6, v0
	v_mul_lo_u32 v4, v0, v3
	v_sub_u32_e32 v4, v6, v4
	v_add_u32_e32 v5, 1, v0
	v_cmp_ge_u32_e32 vcc, v4, v3
	s_nop 1
	v_cndmask_b32_e32 v0, v0, v5, vcc
	v_sub_u32_e32 v5, v4, v3
	v_cndmask_b32_e32 v4, v4, v5, vcc
	v_add_u32_e32 v5, 1, v0
	v_cmp_ge_u32_e32 vcc, v4, v3
	v_add_u32_e32 v4, 1, v6
	s_nop 0
	v_cndmask_b32_e32 v0, v0, v5, vcc
	v_mul_lo_u32 v5, v3, v0
	v_add_u32_e32 v3, v5, v3
	v_cmp_ne_u32_e32 vcc, v4, v3
	s_and_saveexec_b64 s[12:13], vcc
	s_xor_b64 s[38:39], exec, s[12:13]
	s_cbranch_execz .LBB0_490
	buffer_inv sc1
	v_readlane_b32 s12, v255, 10
	v_readlane_b32 s13, v255, 11
	s_waitcnt lgkmcnt(0)
	s_nop 3
	global_load_dword v2, v1, s[12:13] sc1
	s_waitcnt vmcnt(0)
	v_cmp_eq_u32_e32 vcc, v2, v0
	s_and_saveexec_b64 s[40:41], vcc
	s_cbranch_execz .LBB0_489
	s_mov_b32 s3, 1
	s_mov_b64 s[42:43], 0
	s_branch .LBB0_480

; __device__ __forceinline__ unsigned xb_add(unsigned* p, unsigned v) { return __hip_atomic_fetch_add(p, v, __ATOMIC_RELAXED, __HIP_MEMORY_SCOPE_AGENT); }
; __device__ __forceinline__ void xcd_barrier(const XcdBarrier& b) {
;     ...
;             __builtin_amdgcn_fence(__ATOMIC_ACQUIRE, "agent");
;             xb_add(&bar[XB_XGEN(b.x)], 1u);
.LBB0_507:
	s_or_b64 exec, exec, s[38:39]
	s_mov_b64 s[38:39], exec
	v_mbcnt_lo_u32_b32 v0, s38, 0
	v_mbcnt_hi_u32_b32 v0, s39, v0
	v_cmp_eq_u32_e32 vcc, 0, v0
	s_waitcnt vmcnt(0)
	s_and_saveexec_b64 s[40:41], vcc
	s_cbranch_execz .LBB0_509
	s_bcnt1_i32_b64 s3, s[38:39]
	v_readlane_b32 s12, v255, 10
	v_mov_b32_e32 v0, s3
	v_readlane_b32 s13, v255, 11
	s_nop 4
	global_atomic_add v1, v0, s[12:13]

; __device__ __forceinline__ unsigned xb_ld(unsigned* p)              { return __hip_atomic_load(p, __ATOMIC_RELAXED, __HIP_MEMORY_SCOPE_AGENT); }
; __device__ __forceinline__ unsigned xb_add(unsigned* p, unsigned v) { return __hip_atomic_fetch_add(p, v, __ATOMIC_RELAXED, __HIP_MEMORY_SCOPE_AGENT); }
; #define XB_SPIN(cond, bar) do { unsigned _sp = 0; while (cond) { __builtin_amdgcn_s_sleep(1); \
;     if ((++_sp & 255u) == 0u) { if (xb_ld(&(bar)[XB_TMO])) break; if (_sp > XB_SPIN_CAP) { atomicAdd(&(bar)[XB_TMO], 1u); break; } } } } while (0)
; __device__ __forceinline__ void xcd_barrier(const XcdBarrier& b) {
;     ...
;         const unsigned old = xb_add(&bar[XB_XSUB(b.x)], 1u);
;         const unsigned gen = old / nloc;
;         if (old + 1u == (gen + 1u) * nloc) {
;             __builtin_amdgcn_fence(__ATOMIC_RELEASE, "agent");
;             asm volatile("s_waitcnt vmcnt(0)" ::: "memory");
;             const unsigned og = xb_add(&bar[XB_TOP], 1u);
;             const unsigned tg = og / nx;
;             if (og + 1u == (tg + 1u) * nx) xb_add(&bar[XB_TOPGEN], 1u);
;             else XB_SPIN(xb_ld(&bar[XB_TOPGEN]) == tg, bar);
;             __builtin_amdgcn_fence(__ATOMIC_ACQUIRE, "agent");
;             xb_add(&bar[XB_XGEN(b.x)], 1u);
;             asm volatile("s_waitcnt vmcnt(0)" ::: "memory");
;         } else {
;             XB_SPIN(xb_ld(&bar[XB_XGEN(b.x)]) == gen, bar);
.LBB0_621:
	s_or_b64 exec, exec, s[38:39]
	v_cvt_f32_u32_e32 v5, v3
	s_waitcnt vmcnt(0)
	v_readfirstlane_b32 s6, v4
	v_sub_u32_e32 v4, 0, v3
	v_rcp_iflag_f32_e32 v5, v5
	v_add_u32_e32 v6, s6, v0
	v_mul_f32_e32 v5, 0x4f7ffffe, v5
	v_cvt_u32_f32_e32 v5, v5
	v_mul_lo_u32 v0, v4, v5
	v_mul_hi_u32 v0, v5, v0
	v_add_u32_e32 v0, v5, v0
	v_mul_hi_u32 v0, v6, v0
	v_mul_lo_u32 v4, v0, v3
	v_sub_u32_e32 v4, v6, v4
	v_add_u32_e32 v5, 1, v0
	v_cmp_ge_u32_e32 vcc, v4, v3
	s_nop 1
	v_cndmask_b32_e32 v0, v0, v5, vcc
	v_sub_u32_e32 v5, v4, v3
	v_cndmask_b32_e32 v4, v4, v5, vcc
	v_add_u32_e32 v5, 1, v0
	v_cmp_ge_u32_e32 vcc, v4, v3
	v_add_u32_e32 v4, 1, v6
	s_nop 0
	v_cndmask_b32_e32 v0, v0, v5, vcc
	v_mul_lo_u32 v5, v3, v0
	v_add_u32_e32 v3, v5, v3
	v_cmp_ne_u32_e32 vcc, v4, v3
	s_and_saveexec_b64 s[12:13], vcc
	s_xor_b64 s[38:39], exec, s[12:13]
	s_cbranch_execz .LBB0_635
	buffer_inv sc1
	v_readlane_b32 s12, v255, 10
	v_readlane_b32 s13, v255, 11
	s_waitcnt lgkmcnt(0)
	s_nop 3
	global_load_dword v2, v1, s[12:13] sc1
	s_waitcnt vmcnt(0)
	v_cmp_eq_u32_e32 vcc, v2, v0
	s_and_saveexec_b64 s[40:41], vcc
	s_cbranch_execz .LBB0_634
	s_mov_b32 s9, 1
	s_mov_b64 s[42:43], 0
	s_branch .LBB0_625

; __device__ __forceinline__ unsigned xb_add(unsigned* p, unsigned v) { return __hip_atomic_fetch_add(p, v, __ATOMIC_RELAXED, __HIP_MEMORY_SCOPE_AGENT); }
; __device__ __forceinline__ void xcd_barrier(const XcdBarrier& b) {
;     ...
;             __builtin_amdgcn_fence(__ATOMIC_ACQUIRE, "agent");
;             xb_add(&bar[XB_XGEN(b.x)], 1u);
.LBB0_652:
	s_or_b64 exec, exec, s[38:39]
	s_mov_b64 s[38:39], exec
	v_mbcnt_lo_u32_b32 v0, s38, 0
	v_mbcnt_hi_u32_b32 v0, s39, v0
	v_cmp_eq_u32_e32 vcc, 0, v0
	s_waitcnt vmcnt(0)
	s_and_saveexec_b64 s[40:41], vcc
	s_cbranch_execz .LBB0_654
	s_bcnt1_i32_b64 s6, s[38:39]
	v_readlane_b32 s12, v255, 10
	v_mov_b32_e32 v0, s6
	v_readlane_b32 s13, v255, 11
	s_nop 4
	global_atomic_add v1, v0, s[12:13]

; __device__ __forceinline__ unsigned xb_add(unsigned* p, unsigned v) { return __hip_atomic_fetch_add(p, v, __ATOMIC_RELAXED, __HIP_MEMORY_SCOPE_AGENT); }
; __device__ __forceinline__ void xcd_barrier(const XcdBarrier& b) {
;     ...
;             __builtin_amdgcn_fence(__ATOMIC_ACQUIRE, "agent");
;             xb_add(&bar[XB_XGEN(b.x)], 1u);
.LBB0_817:
	s_or_b64 exec, exec, s[38:39]
	s_mov_b64 s[38:39], exec
	v_mbcnt_lo_u32_b32 v0, s38, 0
	v_mbcnt_hi_u32_b32 v0, s39, v0
	v_cmp_eq_u32_e32 vcc, 0, v0
	s_waitcnt vmcnt(0)
	s_and_saveexec_b64 s[40:41], vcc
	s_cbranch_execnz .LBB0_818
	s_getpc_b64 s[98:99]
